# V pass: visit-data loads issued before the row gathers, rows gathered in first-use order and waited per row (vmcnt(38-k)), address formation waits only for the ids (vmcnt(17))
# baseline (speedup 1.0000x reference)
; template <bool VPASS>
; __device__ __forceinline__ void peer_pass(Frame& F, int c, int rank, int nblk) {
;     const unsigned char* T = F.ws + (VPASS ? WS_PV : WS_PU) + (size_t)c * 16384 * 128; const unsigned char* FQc = F.ws + WS_FQ + c * 256;
;     int* PD = (int*)(F.ws + WS_PD) + (size_t)c * NTOK * 128; bf16* PO = (bf16*)(F.ws + WS_PO) + c * 256;
;     const int t0 = rank * NWAVES + F.wave, step = nblk * NWAVES;
;     if (t0 >= NTOK) return;
;     const int nvis = (NTOK - t0 + step - 1) / step;
;     int lane = F.lane; asm volatile("" : "+v"(lane));
;     PeerVisit va = visit_load<VPASS>(F.ws, FQc, t0, lane), vb = va;
;     u32x4 wa[16], wb[16];
;     rows16_load(wa, T, va, lane);
;     if (nvis > 1) vb = visit_load<VPASS>(F.ws, FQc, t0 + step, lane);
; #pragma unroll 1
;     for (int v = 0; v < nvis; v += 2) {
.LBB0_2138:
	s_waitcnt vmcnt(0)
	s_cmp_lt_i32 s50, 1
	s_cbranch_scc1 .LBB0_2156
	s_lshl_b64 s[40:41], s[72:73], 1
	s_add_u32 s62, s64, s40
	s_addc_u32 s63, s65, s41
	s_lshl_b32 s40, s92, 4
	s_lshl_b32 s41, s86, 1
	s_mov_b32 s42, 0.5
	s_lshl_b32 s69, s91, 4
	s_mul_i32 s72, s91, 24
	s_lshl_b32 s73, s91, 5
	s_add_i32 s74, s40, s41
	s_mul_i32 s75, s91, 48
	s_mov_b32 s76, 3
	v_mov_b32_e32 v177, 0
	s_mov_b32 s43, 0x3d800000
	s_branch .LBB0_2142

; template <bool VPASS>
; __device__ __forceinline__ PeerVisit visit_load(const unsigned char* ws, const unsigned char* FQc, int tok, int lane) {
;     PeerVisit v; const int pg = lane >> 3;
;     const u32x4* ep = (const u32x4*)((const int*)(ws + WS_SELE) + (size_t)tok * 128 + pg * 16);
; #pragma unroll
;     for (int q = 0; q < 4; ++q) v.e[q] = ep[q];
;     if (VPASS) { v.x = *(const u32x4*)(ws + WS_CFQ + (size_t)tok * 128 + pg * 16); v.x2 = v.x; v.sc = ((const float*)(ws + WS_CS))[2 * tok]; v.cs = ((const int*)(ws + WS_CS))[2 * tok + 1]; }
;     else { const u32x4* fp = (const u32x4*)(FQc + (size_t)tok * D + (lane & 7) * 32); v.x = fp[0]; v.x2 = fp[1]; v.sc = 0.f; v.cs = 0; }
;     return v;
; }
; __device__ __forceinline__ void rows16_load(u32x4 (&w)[16], const unsigned char* T, const PeerVisit& v, int lane) {
;     const int pc = (lane & 7) * 16;
; #pragma unroll
;     for (int q = 0; q < 4; ++q) {
;         w[4 * q + 0] = *(const u32x4*)(T + (v.e[q].x * 128u + (unsigned)pc)); w[4 * q + 1] = *(const u32x4*)(T + (v.e[q].y * 128u + (unsigned)pc));
;         w[4 * q + 2] = *(const u32x4*)(T + (v.e[q].z * 128u + (unsigned)pc)); w[4 * q + 3] = *(const u32x4*)(T + (v.e[q].w * 128u + (unsigned)pc));
;     }
; }
; template <bool VPASS>
; __device__ __forceinline__ void peer_pass(Frame& F, int c, int rank, int nblk) {
;     ...
;     for (int v = 0; v < nvis; v += 2) {
;         const int tok = t0 + v * step;
;         asm volatile("" : "+v"(lane));
;         PeerVisit vn = va;
;         if (v + 1 < nvis) rows16_load(wb, T, vb, lane);
;         if (v + 2 < nvis) vn = visit_load<VPASS>(F.ws, FQc, tok + 2 * step, lane);
;         if (VPASS) v_compute(wa, va, PO + (size_t)tok * D, lane); else u_compute(wa, va, PD + (size_t)tok * 128, lane);
;         if (v + 1 < nvis) {
;             PeerVisit vm = vb;
;             if (v + 2 < nvis) rows16_load(wa, T, vn, lane);
.LBB0_2141:
	s_add_i32 s76, s76, 2
	s_add_i32 s74, s74, s73
	s_add_i32 s70, s70, s69
	v_mov_b64_e32 v[170:171], v[166:167]
	s_waitcnt vmcnt(17)
	v_mov_b64_e32 v[160:161], v[172:173]
	s_cmp_lt_i32 s77, s50
	v_mov_b32_e32 v183, v181
	v_mov_b32_e32 v182, v180
	v_mov_b64_e32 v[168:169], v[164:165]
	s_waitcnt vmcnt(17)
	v_mov_b32_e32 v179, v185
	v_mov_b32_e32 v178, v184
	v_mov_b64_e32 v[162:163], v[174:175]
	s_cbranch_scc0 .LBB0_2156
.LBB0_2142:
	s_add_i32 s40, s76, -2
	s_cmp_lt_i32 s40, s50
	s_cselect_b64 s[44:45], -1, 0
	s_cmp_ge_i32 s40, s50
.LBB0_2144:
	s_add_i32 s77, s76, -1
	s_cmp_lt_i32 s77, s50
	v_mov_b64_e32 v[164:165], v[168:169]
	s_cselect_b64 s[46:47], -1, 0
	s_cmp_ge_i32 s77, s50
	v_mov_b32_e32 v181, v183
	v_mov_b32_e32 v180, v182
	v_mov_b64_e32 v[166:167], v[170:171]
	s_cbranch_scc1 .Lmy_vA_skip
	s_add_i32 s40, s69, s70
	s_ashr_i32 s41, s40, 31
	s_lshl_b64 s[48:49], s[40:41], 7
	s_lshl_b64 s[40:41], s[40:41], 9
	v_lshlrev_b32_e32 v0, 1, v186
	s_add_u32 s40, s51, s40
	v_and_b32_e32 v164, -16, v0
	s_addc_u32 s41, s55, s41
	v_ashrrev_i32_e32 v165, 31, v164
	v_lshl_add_u64 v[12:13], v[164:165], 2, s[40:41]
	s_add_u32 s40, s66, s48
	s_addc_u32 s41, s67, s49
	v_lshl_add_u64 v[164:165], s[40:41], 0, v[164:165]
	s_add_i32 s40, s73, s74
	s_ashr_i32 s41, s40, 31
	global_load_dwordx4 v[0:3], v[12:13], off offset:48
	global_load_dwordx4 v[4:7], v[12:13], off offset:32
	global_load_dwordx4 v[8:11], v[12:13], off offset:16
	s_nop 0
	global_load_dwordx4 v[12:15], v[12:13], off
	s_lshl_b64 s[40:41], s[40:41], 2
	s_add_u32 s40, s61, s40
	s_addc_u32 s41, s68, s41
	global_load_dwordx4 v[164:167], v[164:165], off
	s_nop 0
	global_load_dwordx2 v[180:181], v177, s[40:41]
.Lmy_vA_skip:
	s_and_b64 vcc, exec, s[44:45]
	s_cbranch_vccz .Lmy_rA_skip
	v_lshlrev_b32_e32 v96, 4, v186
	v_and_b32_e32 v152, 0x70, v96
	v_lshl_or_b32 v96, v92, 7, v152
	v_lshl_or_b32 v100, v93, 7, v152
	v_lshl_or_b32 v104, v94, 7, v152
	v_lshl_or_b32 v108, v95, 7, v152
	v_lshl_or_b32 v112, v76, 7, v152
	v_lshl_or_b32 v116, v77, 7, v152
	v_lshl_or_b32 v120, v78, 7, v152
	v_lshl_or_b32 v124, v79, 7, v152
	v_lshl_or_b32 v128, v72, 7, v152
	v_lshl_or_b32 v132, v73, 7, v152
	v_lshl_or_b32 v136, v74, 7, v152
	v_lshl_or_b32 v140, v75, 7, v152
	v_lshl_or_b32 v144, v88, 7, v152
	v_lshl_or_b32 v148, v89, 7, v152
	v_lshl_or_b32 v153, v90, 7, v152
	v_lshl_or_b32 v156, v91, 7, v152
	global_load_dwordx4 v[96:99], v96, s[2:3]
	s_nop 0
	global_load_dwordx4 v[144:147], v144, s[2:3]
	s_nop 0
	global_load_dwordx4 v[152:155], v153, s[2:3]
	s_nop 0
	global_load_dwordx4 v[148:151], v148, s[2:3]
	s_nop 0
	global_load_dwordx4 v[100:103], v100, s[2:3]
	s_nop 0
	global_load_dwordx4 v[156:159], v156, s[2:3]
	s_nop 0
	global_load_dwordx4 v[104:107], v104, s[2:3]
	s_nop 0
	global_load_dwordx4 v[108:111], v108, s[2:3]
	s_nop 0
	global_load_dwordx4 v[140:143], v140, s[2:3]
	s_nop 0
	global_load_dwordx4 v[112:115], v112, s[2:3]
	s_nop 0
	global_load_dwordx4 v[116:119], v116, s[2:3]
	s_nop 0
	global_load_dwordx4 v[120:123], v120, s[2:3]
	s_nop 0
	global_load_dwordx4 v[124:127], v124, s[2:3]
	s_nop 0
	global_load_dwordx4 v[136:139], v136, s[2:3]
	s_nop 0
	global_load_dwordx4 v[128:131], v128, s[2:3]
	s_nop 0
	global_load_dwordx4 v[132:135], v132, s[2:3]
	s_nop 0
.Lmy_rA_skip:
	s_and_b64 vcc, exec, s[46:47]
	s_cbranch_vccnz .LBB0_2146
	s_waitcnt vmcnt(0)
.LBB0_2146:
	v_lshlrev_b32_e32 v176, 3, v186
	v_lshlrev_b32_e64 v172, v176, 12
	v_xor_b32_e32 v189, 0xc0c0c0c, v172
	v_perm_b32 v184, 0, v168, v189
	s_waitcnt vmcnt(38)
	v_and_b32_e32 v185, 0xf0f0f0f0, v16
	v_and_b32_e32 v187, 0xf0f0f0f0, v18
	s_waitcnt vmcnt(37)
	v_and_b32_e32 v191, 0xf0f0f0f0, v66
	s_waitcnt vmcnt(36)
	v_and_b32_e32 v224, 0xf0f0f0f0, v82
	v_mfma_i32_4x4x4_16b_i8 v[192:195], v184, v185, 0
	v_and_b32_e32 v185, 0xf0f0f0f0, v17
	v_mfma_i32_4x4x4_16b_i8 v[172:175], v184, v16, 0
	v_and_b32_e32 v220, 0xf0f0f0f0, v67
	v_mfma_i32_4x4x4_16b_i8 v[200:203], v184, v185, 0
	v_lshlrev_b32_e64 v185, v176, 13
	v_xor_b32_e32 v190, 0xc0c0c0c, v185
	v_and_b32_e32 v185, 0xf0f0f0f0, v19
	v_mfma_i32_4x4x4_16b_i8 v[196:199], v184, v17, 0
	v_perm_b32 v221, 0, v171, v190
	v_mfma_i32_4x4x4_16b_i8 v[204:207], v184, v18, 0
	s_waitcnt vmcnt(35)
	v_and_b32_e32 v227, 0xf0f0f0f0, v84
	v_mfma_i32_4x4x4_16b_i8 v[208:211], v184, v187, 0
	s_waitcnt vmcnt(34)
	v_and_b32_e32 v187, 0xf0f0f0f0, v22
	v_mfma_i32_4x4x4_16b_i8 v[212:215], v184, v19, 0
	s_waitcnt vmcnt(33)
	v_and_b32_e32 v222, 0xf0f0f0f0, v69
	v_mfma_i32_4x4x4_16b_i8 v[216:219], v184, v185, 0
	v_perm_b32 v184, 0, v168, v190
	v_and_b32_e32 v185, 0xf0f0f0f0, v20
	v_and_b32_e32 v223, 0xf0f0f0f0, v81
	v_mfma_i32_4x4x4_16b_i8 v[172:175], v184, v20, v[172:175]
	v_and_b32_e32 v225, 0xf0f0f0f0, v83
	v_mfma_i32_4x4x4_16b_i8 v[192:195], v184, v185, v[192:195]
	v_and_b32_e32 v185, 0xf0f0f0f0, v21
	v_mfma_i32_4x4x4_16b_i8 v[196:199], v184, v21, v[196:199]
	v_and_b32_e32 v228, 0xf0f0f0f0, v85
	v_mfma_i32_4x4x4_16b_i8 v[200:203], v184, v185, v[200:203]
	v_lshlrev_b32_e64 v185, v176, 14
	v_xor_b32_e32 v188, 0xc0c0c0c, v185
	v_and_b32_e32 v185, 0xf0f0f0f0, v23
	v_mfma_i32_4x4x4_16b_i8 v[204:207], v184, v22, v[204:207]
	v_lshlrev_b32_e64 v176, v176, 15
	v_mfma_i32_4x4x4_16b_i8 v[208:211], v184, v187, v[208:211]
	v_xor_b32_e32 v187, 0xc0c0c0c, v176
	v_mfma_i32_4x4x4_16b_i8 v[212:215], v184, v23, v[212:215]
	s_waitcnt vmcnt(32)
	v_and_b32_e32 v176, 0xf0f0f0f0, v27
	v_mfma_i32_4x4x4_16b_i8 v[216:219], v184, v185, v[216:219]
	v_perm_b32 v184, 0, v168, v188
	v_perm_b32 v168, 0, v168, v187
	v_and_b32_e32 v185, 0xf0f0f0f0, v24
	v_mfma_i32_4x4x4_16b_i8 v[216:219], v184, v176, v[216:219]
	s_waitcnt vmcnt(31)
; __device__ __forceinline__ void v_compute(const u32x4 (&w)[16], const PeerVisit& v, bf16* po, int lane) {
;     ...
;     for (int it = 0; it < 16; ++it) {
;         const int A = (int)__builtin_amdgcn_perm(0u, cq[it >> 2], selq[it & 3]);
; #pragma unroll
;         for (int q = 0; q < 4; ++q) {
;             a1[q] = __builtin_amdgcn_mfma_i32_4x4x4i8(A, (int)w[it][q], a1[q], 0, 0, 0);
;             a2[q] = __builtin_amdgcn_mfma_i32_4x4x4i8(A, (int)(w[it][q] & 0xF0F0F0F0u), a2[q], 0, 0, 0);
;         }
;     }
	v_and_b32_e32 v176, 0xf0f0f0f0, v28
	v_mfma_i32_4x4x4_16b_i8 v[192:195], v184, v185, v[192:195]
	v_and_b32_e32 v185, 0xf0f0f0f0, v25
	v_mfma_i32_4x4x4_16b_i8 v[172:175], v184, v24, v[172:175]
	v_perm_b32 v226, 0, v171, v187
	v_mfma_i32_4x4x4_16b_i8 v[200:203], v184, v185, v[200:203]
	v_and_b32_e32 v185, 0xf0f0f0f0, v26
	v_mfma_i32_4x4x4_16b_i8 v[192:195], v168, v176, v[192:195]
	v_and_b32_e32 v176, 0xf0f0f0f0, v29
	v_mfma_i32_4x4x4_16b_i8 v[208:211], v184, v185, v[208:211]
	v_and_b32_e32 v185, 0xf0f0f0f0, v64
	v_mfma_i32_4x4x4_16b_i8 v[196:199], v184, v25, v[196:199]
	v_mfma_i32_4x4x4_16b_i8 v[204:207], v184, v26, v[204:207]
	v_mfma_i32_4x4x4_16b_i8 v[212:215], v184, v27, v[212:215]
	s_waitcnt vmcnt(30)
	v_and_b32_e32 v184, 0xf0f0f0f0, v61
	v_mfma_i32_4x4x4_16b_i8 v[200:203], v168, v176, v[200:203]
	v_and_b32_e32 v176, 0xf0f0f0f0, v30
	v_mfma_i32_4x4x4_16b_i8 v[172:175], v168, v28, v[172:175]
	s_nop 0
	v_mfma_i32_4x4x4_16b_i8 v[208:211], v168, v176, v[208:211]
	v_and_b32_e32 v176, 0xf0f0f0f0, v31
	v_mfma_i32_4x4x4_16b_i8 v[196:199], v168, v29, v[196:199]
	v_mfma_i32_4x4x4_16b_i8 v[204:207], v168, v30, v[204:207]
	v_mfma_i32_4x4x4_16b_i8 v[212:215], v168, v31, v[212:215]
	v_mfma_i32_4x4x4_16b_i8 v[216:219], v168, v176, v[216:219]
	v_perm_b32 v168, 0, v169, v189
	s_waitcnt vmcnt(29)
	v_and_b32_e32 v176, 0xf0f0f0f0, v32
	s_nop 0
	v_mfma_i32_4x4x4_16b_i8 v[172:175], v168, v32, v[172:175]
	v_mfma_i32_4x4x4_16b_i8 v[192:195], v168, v176, v[192:195]
	v_and_b32_e32 v176, 0xf0f0f0f0, v33
	v_mfma_i32_4x4x4_16b_i8 v[196:199], v168, v33, v[196:199]
	s_nop 0
	v_mfma_i32_4x4x4_16b_i8 v[200:203], v168, v176, v[200:203]
	v_and_b32_e32 v176, 0xf0f0f0f0, v34
	v_mfma_i32_4x4x4_16b_i8 v[204:207], v168, v34, v[204:207]
	s_nop 0
	v_mfma_i32_4x4x4_16b_i8 v[208:211], v168, v176, v[208:211]
	v_and_b32_e32 v176, 0xf0f0f0f0, v35
	v_mfma_i32_4x4x4_16b_i8 v[212:215], v168, v35, v[212:215]
	s_nop 0
	v_mfma_i32_4x4x4_16b_i8 v[216:219], v168, v176, v[216:219]
	v_perm_b32 v168, 0, v169, v190
	s_waitcnt vmcnt(28)
	v_and_b32_e32 v176, 0xf0f0f0f0, v36
	s_nop 0
	v_mfma_i32_4x4x4_16b_i8 v[172:175], v168, v36, v[172:175]
	v_mfma_i32_4x4x4_16b_i8 v[192:195], v168, v176, v[192:195]
	v_and_b32_e32 v176, 0xf0f0f0f0, v37
	v_mfma_i32_4x4x4_16b_i8 v[196:199], v168, v37, v[196:199]
	s_nop 0
	v_mfma_i32_4x4x4_16b_i8 v[200:203], v168, v176, v[200:203]
	v_and_b32_e32 v176, 0xf0f0f0f0, v38
	v_mfma_i32_4x4x4_16b_i8 v[204:207], v168, v38, v[204:207]
	s_nop 0
	v_mfma_i32_4x4x4_16b_i8 v[208:211], v168, v176, v[208:211]
	v_and_b32_e32 v176, 0xf0f0f0f0, v39
	v_mfma_i32_4x4x4_16b_i8 v[212:215], v168, v39, v[212:215]
	s_nop 0
	v_mfma_i32_4x4x4_16b_i8 v[216:219], v168, v176, v[216:219]
	v_perm_b32 v168, 0, v169, v188
	s_waitcnt vmcnt(27)
	v_and_b32_e32 v176, 0xf0f0f0f0, v40
	s_nop 0
	v_mfma_i32_4x4x4_16b_i8 v[172:175], v168, v40, v[172:175]
	v_mfma_i32_4x4x4_16b_i8 v[192:195], v168, v176, v[192:195]
	v_and_b32_e32 v176, 0xf0f0f0f0, v41
	v_mfma_i32_4x4x4_16b_i8 v[196:199], v168, v41, v[196:199]
	s_nop 0
	v_mfma_i32_4x4x4_16b_i8 v[200:203], v168, v176, v[200:203]
	v_and_b32_e32 v176, 0xf0f0f0f0, v42
	v_mfma_i32_4x4x4_16b_i8 v[204:207], v168, v42, v[204:207]
	s_nop 0
	v_mfma_i32_4x4x4_16b_i8 v[208:211], v168, v176, v[208:211]
	v_and_b32_e32 v176, 0xf0f0f0f0, v43
	v_mfma_i32_4x4x4_16b_i8 v[212:215], v168, v43, v[212:215]
	s_nop 0
	v_mfma_i32_4x4x4_16b_i8 v[216:219], v168, v176, v[216:219]
	v_perm_b32 v168, 0, v169, v187
	s_waitcnt vmcnt(26)
	v_and_b32_e32 v169, 0xf0f0f0f0, v44
	s_waitcnt vmcnt(25)
	v_and_b32_e32 v176, 0xf0f0f0f0, v58
	v_mfma_i32_4x4x4_16b_i8 v[172:175], v168, v44, v[172:175]
	v_mfma_i32_4x4x4_16b_i8 v[192:195], v168, v169, v[192:195]
	v_and_b32_e32 v169, 0xf0f0f0f0, v45
	v_mfma_i32_4x4x4_16b_i8 v[196:199], v168, v45, v[196:199]
	s_nop 0
	v_mfma_i32_4x4x4_16b_i8 v[200:203], v168, v169, v[200:203]
	v_and_b32_e32 v169, 0xf0f0f0f0, v46
	v_mfma_i32_4x4x4_16b_i8 v[204:207], v168, v46, v[204:207]
	s_nop 0
	v_mfma_i32_4x4x4_16b_i8 v[208:211], v168, v169, v[208:211]
	v_and_b32_e32 v169, 0xf0f0f0f0, v47
	v_mfma_i32_4x4x4_16b_i8 v[212:215], v168, v47, v[212:215]
	s_nop 0
	v_mfma_i32_4x4x4_16b_i8 v[216:219], v168, v169, v[216:219]
	v_perm_b32 v168, 0, v170, v189
	s_waitcnt vmcnt(24)
	v_and_b32_e32 v169, 0xf0f0f0f0, v48
	s_nop 0
	v_mfma_i32_4x4x4_16b_i8 v[172:175], v168, v48, v[172:175]
	v_mfma_i32_4x4x4_16b_i8 v[192:195], v168, v169, v[192:195]
	v_and_b32_e32 v169, 0xf0f0f0f0, v49
	v_mfma_i32_4x4x4_16b_i8 v[196:199], v168, v49, v[196:199]
	s_nop 0
	v_mfma_i32_4x4x4_16b_i8 v[200:203], v168, v169, v[200:203]
	v_and_b32_e32 v169, 0xf0f0f0f0, v50
	v_mfma_i32_4x4x4_16b_i8 v[204:207], v168, v50, v[204:207]
	s_nop 0
	v_mfma_i32_4x4x4_16b_i8 v[208:211], v168, v169, v[208:211]
	v_and_b32_e32 v169, 0xf0f0f0f0, v51
	v_mfma_i32_4x4x4_16b_i8 v[212:215], v168, v51, v[212:215]
	s_nop 0
	v_mfma_i32_4x4x4_16b_i8 v[216:219], v168, v169, v[216:219]
	v_perm_b32 v168, 0, v170, v190
	s_waitcnt vmcnt(23)
; __device__ __forceinline__ void v_compute(const u32x4 (&w)[16], const PeerVisit& v, bf16* po, int lane) {
;     ...
;     for (int it = 0; it < 16; ++it) {
;         const int A = (int)__builtin_amdgcn_perm(0u, cq[it >> 2], selq[it & 3]);
; #pragma unroll
;         for (int q = 0; q < 4; ++q) {
;             a1[q] = __builtin_amdgcn_mfma_i32_4x4x4i8(A, (int)w[it][q], a1[q], 0, 0, 0);
;             a2[q] = __builtin_amdgcn_mfma_i32_4x4x4i8(A, (int)(w[it][q] & 0xF0F0F0F0u), a2[q], 0, 0, 0);
;         }
;     }
;     int r1[2][4], r2[2][4];
; #pragma unroll
;     for (int jj = 0; jj < 2; ++jj)
; #pragma unroll
;         for (int i = 0; i < 4; ++i) {
;             const auto t1 = __builtin_amdgcn_permlane32_swap((unsigned)a1[jj][i], (unsigned)a1[jj + 2][i], false, false); r1[jj][i] = (int)t1[0] + (int)t1[1];
;             const auto t2 = __builtin_amdgcn_permlane32_swap((unsigned)a2[jj][i], (unsigned)a2[jj + 2][i], false, false); r2[jj][i] = (int)t2[0] + (int)t2[1];
;         }
;     int s1[4], s2[4];
; #pragma unroll
;     for (int i = 0; i < 4; ++i) {
;         const auto t1 = __builtin_amdgcn_permlane16_swap((unsigned)r1[0][i], (unsigned)r1[1][i], false, false); s1[i] = (int)t1[0] + (int)t1[1];
;         const auto t2 = __builtin_amdgcn_permlane16_swap((unsigned)r2[0][i], (unsigned)r2[1][i], false, false); s2[i] = (int)t2[0] + (int)t2[1];
;         s1[i] += __builtin_amdgcn_update_dpp(0, s1[i], 0x128, 0xF, 0xF, false);
;         s2[i] += __builtin_amdgcn_update_dpp(0, s2[i], 0x128, 0xF, 0xF, false);
;     }
;     if (!(lane & 8)) {
	v_and_b32_e32 v169, 0xf0f0f0f0, v52
	s_nop 0
	v_mfma_i32_4x4x4_16b_i8 v[172:175], v168, v52, v[172:175]
	v_mfma_i32_4x4x4_16b_i8 v[192:195], v168, v169, v[192:195]
	v_and_b32_e32 v169, 0xf0f0f0f0, v53
	v_mfma_i32_4x4x4_16b_i8 v[196:199], v168, v53, v[196:199]
	s_nop 0
	v_mfma_i32_4x4x4_16b_i8 v[200:203], v168, v169, v[200:203]
	v_and_b32_e32 v169, 0xf0f0f0f0, v54
	v_mfma_i32_4x4x4_16b_i8 v[204:207], v168, v54, v[204:207]
	s_nop 0
	v_mfma_i32_4x4x4_16b_i8 v[208:211], v168, v169, v[208:211]
	v_and_b32_e32 v169, 0xf0f0f0f0, v55
	v_mfma_i32_4x4x4_16b_i8 v[212:215], v168, v55, v[212:215]
	s_nop 0
	v_mfma_i32_4x4x4_16b_i8 v[216:219], v168, v169, v[216:219]
	v_perm_b32 v168, 0, v170, v188
	v_perm_b32 v170, 0, v170, v187
	v_and_b32_e32 v169, 0xf0f0f0f0, v56
	v_mfma_i32_4x4x4_16b_i8 v[208:211], v168, v176, v[208:211]
	v_and_b32_e32 v176, 0xf0f0f0f0, v60
	v_mfma_i32_4x4x4_16b_i8 v[192:195], v168, v169, v[192:195]
	v_and_b32_e32 v169, 0xf0f0f0f0, v57
	v_mfma_i32_4x4x4_16b_i8 v[172:175], v168, v56, v[172:175]
	v_mfma_i32_4x4x4_16b_i8 v[192:195], v170, v176, v[192:195]
	v_perm_b32 v176, 0, v171, v189
	v_mfma_i32_4x4x4_16b_i8 v[200:203], v168, v169, v[200:203]
	v_and_b32_e32 v169, 0xf0f0f0f0, v59
	v_mfma_i32_4x4x4_16b_i8 v[196:199], v168, v57, v[196:199]
	v_mfma_i32_4x4x4_16b_i8 v[204:207], v168, v58, v[204:207]
	v_mfma_i32_4x4x4_16b_i8 v[212:215], v168, v59, v[212:215]
	v_mfma_i32_4x4x4_16b_i8 v[216:219], v168, v169, v[216:219]
	v_and_b32_e32 v168, 0xf0f0f0f0, v62
	v_mfma_i32_4x4x4_16b_i8 v[204:207], v170, v62, v[204:207]
	v_and_b32_e32 v169, 0xf0f0f0f0, v63
	v_mfma_i32_4x4x4_16b_i8 v[208:211], v170, v168, v[208:211]
	v_and_b32_e32 v168, 0xf0f0f0f0, v68
	v_mfma_i32_4x4x4_16b_i8 v[172:175], v170, v60, v[172:175]
	v_mfma_i32_4x4x4_16b_i8 v[208:211], v176, v191, v[208:211]
	v_perm_b32 v191, 0, v171, v188
	v_mfma_i32_4x4x4_16b_i8 v[192:195], v176, v185, v[192:195]
	v_and_b32_e32 v185, 0xf0f0f0f0, v71
	v_mfma_i32_4x4x4_16b_i8 v[204:207], v176, v66, v[204:207]
	v_mfma_i32_4x4x4_16b_i8 v[216:219], v170, v169, v[216:219]
	v_and_b32_e32 v169, 0xf0f0f0f0, v70
	v_mfma_i32_4x4x4_16b_i8 v[172:175], v176, v64, v[172:175]
	v_mfma_i32_4x4x4_16b_i8 v[192:195], v221, v168, v[192:195]
	v_mfma_i32_4x4x4_16b_i8 v[204:207], v221, v70, v[204:207]
	v_mfma_i32_4x4x4_16b_i8 v[208:211], v221, v169, v[208:211]
	v_mfma_i32_4x4x4_16b_i8 v[196:199], v170, v61, v[196:199]
	v_mfma_i32_4x4x4_16b_i8 v[200:203], v170, v184, v[200:203]
	v_and_b32_e32 v184, 0xf0f0f0f0, v65
	v_mfma_i32_4x4x4_16b_i8 v[212:215], v170, v63, v[212:215]
	v_and_b32_e32 v170, 0xf0f0f0f0, v80
	v_mfma_i32_4x4x4_16b_i8 v[172:175], v221, v68, v[172:175]
	s_nop 0
	v_mfma_i32_4x4x4_16b_i8 v[168:171], v191, v170, v[192:195]
	v_mfma_i32_4x4x4_16b_i8 v[192:195], v191, v82, v[204:207]
	v_mfma_i32_4x4x4_16b_i8 v[204:207], v191, v224, v[208:211]
	v_and_b32_e32 v224, 0xf0f0f0f0, v87
	v_mfma_i32_4x4x4_16b_i8 v[172:175], v191, v80, v[172:175]
	v_and_b32_e32 v208, 0xf0f0f0f0, v86
	v_mfma_i32_4x4x4_16b_i8 v[196:199], v176, v65, v[196:199]
	s_nop 0
	v_mfma_i32_4x4x4_16b_i8 v[204:207], v226, v208, v[204:207]
	v_mfma_i32_4x4x4_16b_i8 v[200:203], v176, v184, v[200:203]
	v_mfma_i32_4x4x4_16b_i8 v[208:211], v176, v67, v[212:215]
	v_mfma_i32_4x4x4_16b_i8 v[212:215], v176, v220, v[216:219]
	v_mfma_i32_4x4x4_16b_i8 v[172:175], v226, v84, v[172:175]
	v_mfma_i32_4x4x4_16b_i8 v[192:195], v226, v86, v[192:195]
	v_mfma_i32_4x4x4_16b_i8 v[168:171], v226, v227, v[168:171]
	v_mfma_i32_4x4x4_16b_i8 v[196:199], v221, v69, v[196:199]
	v_mfma_i32_4x4x4_16b_i8 v[200:203], v221, v222, v[200:203]
	s_nop 1
	v_permlane32_swap_b32_e32 v172, v192
	v_mfma_i32_4x4x4_16b_i8 v[208:211], v221, v71, v[208:211]
	v_permlane32_swap_b32_e32 v173, v193
	v_mfma_i32_4x4x4_16b_i8 v[212:215], v221, v185, v[212:215]
	v_permlane32_swap_b32_e32 v169, v205
	v_permlane32_swap_b32_e32 v174, v194
	v_permlane32_swap_b32_e32 v170, v206
	v_permlane32_swap_b32_e32 v175, v195
	v_add_u32_e32 v227, v172, v192
	v_add_u32_e32 v184, v173, v193
	v_add_u32_e32 v176, v169, v205
	v_add_u32_e32 v205, v174, v194
	v_mfma_i32_4x4x4_16b_i8 v[196:199], v191, v81, v[196:199]
	v_add_u32_e32 v185, v170, v206
	v_mfma_i32_4x4x4_16b_i8 v[200:203], v191, v223, v[200:203]
	v_add_u32_e32 v206, v175, v195
	v_mfma_i32_4x4x4_16b_i8 v[208:211], v191, v83, v[208:211]
	v_permlane32_swap_b32_e32 v168, v204
	v_mfma_i32_4x4x4_16b_i8 v[172:175], v191, v225, v[212:215]
	v_permlane32_swap_b32_e32 v171, v207
	v_add_u32_e32 v204, v168, v204
	v_mfma_i32_4x4x4_16b_i8 v[192:195], v226, v85, v[196:199]
	v_add_u32_e32 v207, v171, v207
	v_mfma_i32_4x4x4_16b_i8 v[168:171], v226, v87, v[208:211]
	v_mfma_i32_4x4x4_16b_i8 v[196:199], v226, v228, v[200:203]
	v_mfma_i32_4x4x4_16b_i8 v[172:175], v226, v224, v[172:175]
	s_nop 2
	v_permlane32_swap_b32_e32 v192, v168
	v_permlane32_swap_b32_e32 v193, v169
	v_permlane32_swap_b32_e32 v196, v172
	v_permlane32_swap_b32_e32 v197, v173
	v_permlane32_swap_b32_e32 v194, v170
	v_permlane32_swap_b32_e32 v198, v174
	v_permlane32_swap_b32_e32 v195, v171
	v_permlane32_swap_b32_e32 v199, v175
	v_add_u32_e32 v168, v192, v168
	v_add_u32_e32 v172, v196, v172
	v_add_u32_e32 v191, v193, v169
	v_add_u32_e32 v173, v197, v173
	v_add_u32_e32 v192, v194, v170
	v_add_u32_e32 v193, v198, v174
	v_add_u32_e32 v194, v195, v171
	v_add_u32_e32 v195, v199, v175
	v_permlane16_swap_b32_e32 v227, v168
	v_permlane16_swap_b32_e32 v204, v172
	v_permlane16_swap_b32_e32 v184, v191
	v_permlane16_swap_b32_e32 v176, v173
	v_permlane16_swap_b32_e32 v205, v192
	v_permlane16_swap_b32_e32 v185, v193
	v_permlane16_swap_b32_e32 v206, v194
	v_permlane16_swap_b32_e32 v207, v195
	v_add_u32_e32 v168, v227, v168
	v_add_u32_e32 v169, v204, v172
	v_mov_b32_e32 v170, 0
	v_mov_b32_e32 v171, 0
	v_add_u32_e32 v172, v184, v191
	v_add_u32_e32 v173, v176, v173
	v_mov_b32_e32 v174, 0
	v_mov_b32_e32 v175, 0
	v_add_u32_e32 v176, v205, v192
	v_add_u32_e32 v184, v185, v193
	v_mov_b32_e32 v185, 0
	v_mov_b32_e32 v191, 0
	v_add_u32_e32 v192, v206, v194
	v_add_u32_e32 v193, v207, v195
	v_mov_b32_e32 v194, 0
	v_mov_b32_e32 v195, 0
	v_and_b32_e32 v196, 8, v186
	v_mov_b32_dpp v170, v168 row_ror:8 row_mask:0xf bank_mask:0xf
	v_mov_b32_dpp v171, v169 row_ror:8 row_mask:0xf bank_mask:0xf
	v_mov_b32_dpp v174, v172 row_ror:8 row_mask:0xf bank_mask:0xf
	v_mov_b32_dpp v175, v173 row_ror:8 row_mask:0xf bank_mask:0xf
	v_mov_b32_dpp v185, v176 row_ror:8 row_mask:0xf bank_mask:0xf
	v_mov_b32_dpp v191, v184 row_ror:8 row_mask:0xf bank_mask:0xf
	v_mov_b32_dpp v194, v192 row_ror:8 row_mask:0xf bank_mask:0xf
	v_mov_b32_dpp v195, v193 row_ror:8 row_mask:0xf bank_mask:0xf
	v_cmp_eq_u32_e64 s[40:41], 0, v196
	s_and_saveexec_b64 s[48:49], s[40:41]
	s_cbranch_execz .LBB0_2148
; __device__ __forceinline__ unsigned cvt_pk_bf16(float lo, float hi) { unsigned r; asm volatile("v_cvt_pk_bf16_f32 %0, %1, %2" : "=v"(r) : "v"(lo), "v"(hi)); return r; }
; __device__ __forceinline__ void v_compute(const u32x4 (&w)[16], const PeerVisit& v, bf16* po, int lane) {
;     ...
;     if (!(lane & 8)) {
;         const float csf = (float)v.cs; float lo[4], hi[4];
; #pragma unroll
;         for (int i = 0; i < 4; ++i) { lo[i] = ((float)(s1[i] - s2[i]) - 7.5f * csf) * v.sc; hi[i] = ((float)s2[i] * 0.0625f + 0.5f * csf) * v.sc; }
;         u32x4 o;
;         o.x = cvt_pk_bf16(lo[0], lo[1]); o.y = cvt_pk_bf16(lo[2], lo[3]); o.z = cvt_pk_bf16(hi[0], hi[1]); o.w = cvt_pk_bf16(hi[2], hi[3]);
;         __builtin_nontemporal_store(o, (u32x4*)(po + (lane & 7) * 32 + 8 * (((lane >> 4) & 1) + 2 * (lane >> 5))));
;     }
; template <bool VPASS>
; __device__ __forceinline__ void peer_pass(Frame& F, int c, int rank, int nblk) {
;     ...
;         if (v + 1 < nvis) {
;             PeerVisit vm = vb;
;             if (v + 2 < nvis) rows16_load(wa, T, vn, lane);
;             if (v + 3 < nvis) vm = visit_load<VPASS>(F.ws, FQc, tok + 3 * step, lane);
;             if (VPASS) v_compute(wb, vb, PO + (size_t)(tok + step) * D, lane); else u_compute(wb, vb, PD + (size_t)(tok + step) * 128, lane);
	v_add_u32_e32 v169, v171, v169
	v_add_u32_e32 v168, v170, v168
	v_add_u32_e32 v173, v175, v173
	v_add_u32_e32 v172, v174, v172
	v_sub_u32_e32 v168, v168, v169
	v_cvt_f32_i32_e32 v170, v168
	v_sub_u32_e32 v168, v172, v173
	v_add_u32_e32 v184, v191, v184
	v_add_u32_e32 v176, v185, v176
	v_cvt_f32_i32_e32 v172, v168
	v_cvt_f32_i32_e32 v168, v183
	v_cvt_f32_i32_e32 v174, v169
	v_sub_u32_e32 v171, v176, v184
	v_cvt_f32_i32_e32 v169, v184
	v_cvt_f32_i32_e32 v175, v171
	v_cvt_f32_i32_e32 v173, v173
	v_fmac_f32_e32 v170, 0xc0f00000, v168
	v_mul_f32_e32 v176, v182, v170
	v_pk_mul_f32 v[170:171], v[168:169], s[42:43]
	v_add_u32_e32 v193, v195, v193
	v_add_u32_e32 v192, v194, v192
	v_fmamk_f32 v169, v174, 0x3d800000, v170
	v_fmac_f32_e32 v172, 0xc0f00000, v168
	v_fmac_f32_e32 v175, 0xc0f00000, v168
	v_mul_f32_e32 v174, v182, v169
	v_mul_f32_e32 v169, v182, v172
	v_fmamk_f32 v172, v173, 0x3d800000, v170
	v_mul_f32_e32 v173, v182, v175
	v_sub_u32_e32 v175, v192, v193
	v_cvt_f32_i32_e32 v175, v175
	v_cvt_f32_i32_e32 v183, v193
	s_ashr_i32 s71, s70, 31
	v_add_f32_e32 v171, v170, v171
	v_fmac_f32_e32 v175, 0xc0f00000, v168
	v_mul_f32_e32 v175, v182, v175
	v_fmac_f32_e32 v170, 0x3d800000, v183
	v_cvt_pk_bf16_f32 v168, v176, v169
	v_cvt_pk_bf16_f32 v169, v173, v175
	v_ashrrev_i32_e32 v175, 4, v186
	s_lshl_b64 s[78:79], s[70:71], 12
	v_mul_f32_e32 v172, v182, v172
	v_mul_f32_e32 v171, v182, v171
	v_mul_f32_e32 v182, v182, v170
	v_cvt_pk_bf16_f32 v170, v174, v172
	v_lshrrev_b32_e32 v174, 4, v186
	v_and_b32_e32 v175, 0x1ffffffe, v175
	s_add_u32 s78, s62, s78
	v_lshlrev_b32_e32 v172, 6, v186
	v_and_or_b32 v174, v174, 1, v175
	s_addc_u32 s79, s63, s79
	v_and_b32_e32 v176, 0x1c0, v172
	v_lshlrev_b32_e32 v174, 3, v174
	v_lshl_add_u64 v[172:173], s[78:79], 0, v[176:177]
	v_ashrrev_i32_e32 v175, 31, v174
	v_lshl_add_u64 v[172:173], v[174:175], 1, v[172:173]
	v_cvt_pk_bf16_f32 v171, v171, v182
	global_store_dwordx4 v[172:173], v[168:171], off nt
.LBB0_2148:
	s_or_b64 exec, exec, s[48:49]
	s_waitcnt vmcnt(17)
	s_andn2_b64 vcc, exec, s[44:45]
	s_cbranch_vccnz .LBB0_2155
	s_mov_b64 s[98:99], s[46:47]
.LBB0_2151:
	v_mov_b64_e32 v[174:175], v[162:163]
	v_mov_b32_e32 v185, v179
	v_mov_b32_e32 v184, v178
	v_mov_b64_e32 v[172:173], v[160:161]
	s_cmp_ge_i32 s76, s50
	s_cselect_b64 s[100:101], 0, -1
	s_cbranch_scc1 .Lmy_vB_skip
	s_add_i32 s44, s72, s70
	s_ashr_i32 s45, s44, 31
	s_lshl_b64 s[46:47], s[44:45], 7
	s_lshl_b64 s[44:45], s[44:45], 9
	v_lshlrev_b32_e32 v72, 1, v186
	s_add_u32 s44, s51, s44
	v_and_b32_e32 v168, -16, v72
	s_addc_u32 s45, s55, s45
	v_ashrrev_i32_e32 v169, 31, v168
	v_lshl_add_u64 v[92:93], v[168:169], 2, s[44:45]
	s_add_u32 s44, s66, s46
	s_addc_u32 s45, s67, s47
	v_lshl_add_u64 v[168:169], s[44:45], 0, v[168:169]
	s_add_i32 s44, s75, s74
	s_ashr_i32 s45, s44, 31
	global_load_dwordx4 v[88:91], v[92:93], off offset:48
	global_load_dwordx4 v[72:75], v[92:93], off offset:32
	global_load_dwordx4 v[76:79], v[92:93], off offset:16
	s_nop 0
	global_load_dwordx4 v[92:95], v[92:93], off
	s_lshl_b64 s[44:45], s[44:45], 2
	s_add_u32 s44, s61, s44
	s_addc_u32 s45, s68, s45
	global_load_dwordx4 v[172:175], v[168:169], off
	global_load_dwordx2 v[184:185], v177, s[44:45]
.Lmy_vB_skip:
	s_and_b64 vcc, exec, s[98:99]
	s_cbranch_vccz .Lmy_rB_skip
	v_lshlrev_b32_e32 v16, 4, v186
	v_and_b32_e32 v80, 0x70, v16
	v_lshl_or_b32 v16, v12, 7, v80
	v_lshl_or_b32 v20, v13, 7, v80
	v_lshl_or_b32 v24, v14, 7, v80
	v_lshl_or_b32 v28, v15, 7, v80
	v_lshl_or_b32 v32, v8, 7, v80
	v_lshl_or_b32 v36, v9, 7, v80
	v_lshl_or_b32 v40, v10, 7, v80
	v_lshl_or_b32 v44, v11, 7, v80
	v_lshl_or_b32 v48, v4, 7, v80
	v_lshl_or_b32 v52, v5, 7, v80
	v_lshl_or_b32 v56, v6, 7, v80
	v_lshl_or_b32 v60, v7, 7, v80
	v_lshl_or_b32 v64, v0, 7, v80
	v_lshl_or_b32 v68, v1, 7, v80
	v_lshl_or_b32 v81, v2, 7, v80
	v_lshl_or_b32 v84, v3, 7, v80
	global_load_dwordx4 v[16:19], v16, s[2:3]
	s_nop 0
	global_load_dwordx4 v[64:67], v64, s[2:3]
	s_nop 0
	global_load_dwordx4 v[80:83], v81, s[2:3]
	s_nop 0
	global_load_dwordx4 v[84:87], v84, s[2:3]
	s_nop 0
	global_load_dwordx4 v[20:23], v20, s[2:3]
	s_nop 0
	global_load_dwordx4 v[68:71], v68, s[2:3]
	s_nop 0
	global_load_dwordx4 v[24:27], v24, s[2:3]
	s_nop 0
	global_load_dwordx4 v[28:31], v28, s[2:3]
	s_nop 0
	global_load_dwordx4 v[60:63], v60, s[2:3]
	s_nop 0
	global_load_dwordx4 v[32:35], v32, s[2:3]
	s_nop 0
	global_load_dwordx4 v[36:39], v36, s[2:3]
	s_nop 0
	global_load_dwordx4 v[40:43], v40, s[2:3]
	s_nop 0
	global_load_dwordx4 v[44:47], v44, s[2:3]
	s_nop 0
	global_load_dwordx4 v[56:59], v56, s[2:3]
	s_nop 0
	global_load_dwordx4 v[48:51], v48, s[2:3]
	s_nop 0
	global_load_dwordx4 v[52:55], v52, s[2:3]
	s_nop 0
.Lmy_rB_skip:
	s_and_b64 vcc, exec, s[100:101]
	s_cbranch_vccnz .LBB0_2153
	s_waitcnt vmcnt(0)
; __device__ __forceinline__ void v_compute(const u32x4 (&w)[16], const PeerVisit& v, bf16* po, int lane) {
;     ...
;     for (int it = 0; it < 16; ++it) {
;         const int A = (int)__builtin_amdgcn_perm(0u, cq[it >> 2], selq[it & 3]);
; #pragma unroll
;         for (int q = 0; q < 4; ++q) {
;             a1[q] = __builtin_amdgcn_mfma_i32_4x4x4i8(A, (int)w[it][q], a1[q], 0, 0, 0);
;             a2[q] = __builtin_amdgcn_mfma_i32_4x4x4i8(A, (int)(w[it][q] & 0xF0F0F0F0u), a2[q], 0, 0, 0);
;         }
;     }
.LBB0_2153:
	v_perm_b32 v176, 0, v160, v189
	s_waitcnt vmcnt(38)
	v_and_b32_e32 v182, 0xf0f0f0f0, v96
	v_perm_b32 v221, 0, v163, v190
	s_waitcnt vmcnt(37)
	v_and_b32_e32 v183, 0xf0f0f0f0, v144
	v_perm_b32 v223, 0, v163, v188
	v_mfma_i32_4x4x4_16b_i8 v[192:195], v176, v182, 0
	v_and_b32_e32 v182, 0xf0f0f0f0, v97
	v_mfma_i32_4x4x4_16b_i8 v[168:171], v176, v96, 0
	s_waitcnt vmcnt(36)
	v_and_b32_e32 v225, 0xf0f0f0f0, v154
	v_mfma_i32_4x4x4_16b_i8 v[200:203], v176, v182, 0
	v_and_b32_e32 v182, 0xf0f0f0f0, v98
	v_mfma_i32_4x4x4_16b_i8 v[196:199], v176, v97, 0
	v_and_b32_e32 v220, 0xf0f0f0f0, v147
	v_mfma_i32_4x4x4_16b_i8 v[208:211], v176, v182, 0
	v_and_b32_e32 v182, 0xf0f0f0f0, v99
	v_mfma_i32_4x4x4_16b_i8 v[204:207], v176, v98, 0
	s_waitcnt vmcnt(35)
	v_and_b32_e32 v222, 0xf0f0f0f0, v149
	v_mfma_i32_4x4x4_16b_i8 v[212:215], v176, v99, 0
	v_and_b32_e32 v224, 0xf0f0f0f0, v153
	v_mfma_i32_4x4x4_16b_i8 v[216:219], v176, v182, 0
	v_perm_b32 v176, 0, v160, v190
	s_waitcnt vmcnt(34)
	v_and_b32_e32 v182, 0xf0f0f0f0, v100
	v_and_b32_e32 v226, 0xf0f0f0f0, v155
	v_mfma_i32_4x4x4_16b_i8 v[168:171], v176, v100, v[168:171]
	s_waitcnt vmcnt(33)
	v_and_b32_e32 v227, 0xf0f0f0f0, v157
	v_mfma_i32_4x4x4_16b_i8 v[192:195], v176, v182, v[192:195]
	v_and_b32_e32 v182, 0xf0f0f0f0, v101
	v_mfma_i32_4x4x4_16b_i8 v[196:199], v176, v101, v[196:199]
	s_nop 0
	v_mfma_i32_4x4x4_16b_i8 v[200:203], v176, v182, v[200:203]
	v_and_b32_e32 v182, 0xf0f0f0f0, v102
	v_mfma_i32_4x4x4_16b_i8 v[204:207], v176, v102, v[204:207]
	s_nop 0
	v_mfma_i32_4x4x4_16b_i8 v[208:211], v176, v182, v[208:211]
	v_and_b32_e32 v182, 0xf0f0f0f0, v103
	v_mfma_i32_4x4x4_16b_i8 v[212:215], v176, v103, v[212:215]
	s_nop 0
	v_mfma_i32_4x4x4_16b_i8 v[216:219], v176, v182, v[216:219]
	v_perm_b32 v176, 0, v160, v188
	s_waitcnt vmcnt(32)
	v_and_b32_e32 v182, 0xf0f0f0f0, v104
	v_perm_b32 v160, 0, v160, v187
	v_mfma_i32_4x4x4_16b_i8 v[168:171], v176, v104, v[168:171]
	v_mfma_i32_4x4x4_16b_i8 v[192:195], v176, v182, v[192:195]
	v_and_b32_e32 v182, 0xf0f0f0f0, v105
	v_mfma_i32_4x4x4_16b_i8 v[196:199], v176, v105, v[196:199]
	s_nop 0
	v_mfma_i32_4x4x4_16b_i8 v[200:203], v176, v182, v[200:203]
	v_and_b32_e32 v182, 0xf0f0f0f0, v106
	v_mfma_i32_4x4x4_16b_i8 v[204:207], v176, v106, v[204:207]
	s_nop 0
	v_mfma_i32_4x4x4_16b_i8 v[208:211], v176, v182, v[208:211]
	v_and_b32_e32 v182, 0xf0f0f0f0, v107
	v_mfma_i32_4x4x4_16b_i8 v[212:215], v176, v107, v[212:215]
	s_nop 0
	v_mfma_i32_4x4x4_16b_i8 v[216:219], v176, v182, v[216:219]
	s_waitcnt vmcnt(31)
	v_and_b32_e32 v176, 0xf0f0f0f0, v108
	v_mfma_i32_4x4x4_16b_i8 v[168:171], v160, v108, v[168:171]
	s_waitcnt vmcnt(30)
	v_and_b32_e32 v182, 0xf0f0f0f0, v141
	v_mfma_i32_4x4x4_16b_i8 v[192:195], v160, v176, v[192:195]
	v_and_b32_e32 v176, 0xf0f0f0f0, v109
	v_mfma_i32_4x4x4_16b_i8 v[196:199], v160, v109, v[196:199]
	s_nop 0
	v_mfma_i32_4x4x4_16b_i8 v[200:203], v160, v176, v[200:203]
	v_and_b32_e32 v176, 0xf0f0f0f0, v110
	v_mfma_i32_4x4x4_16b_i8 v[204:207], v160, v110, v[204:207]
	s_nop 0
	v_mfma_i32_4x4x4_16b_i8 v[208:211], v160, v176, v[208:211]
	v_and_b32_e32 v176, 0xf0f0f0f0, v111
	v_mfma_i32_4x4x4_16b_i8 v[212:215], v160, v111, v[212:215]
	s_nop 0
	v_mfma_i32_4x4x4_16b_i8 v[216:219], v160, v176, v[216:219]
	v_perm_b32 v160, 0, v161, v189
	s_waitcnt vmcnt(29)
	v_and_b32_e32 v176, 0xf0f0f0f0, v112
	s_nop 0
	v_mfma_i32_4x4x4_16b_i8 v[168:171], v160, v112, v[168:171]
	v_mfma_i32_4x4x4_16b_i8 v[192:195], v160, v176, v[192:195]
	v_and_b32_e32 v176, 0xf0f0f0f0, v113
	v_mfma_i32_4x4x4_16b_i8 v[196:199], v160, v113, v[196:199]
	s_nop 0
	v_mfma_i32_4x4x4_16b_i8 v[200:203], v160, v176, v[200:203]
	v_and_b32_e32 v176, 0xf0f0f0f0, v114
	v_mfma_i32_4x4x4_16b_i8 v[204:207], v160, v114, v[204:207]
	s_nop 0
	v_mfma_i32_4x4x4_16b_i8 v[208:211], v160, v176, v[208:211]
	v_and_b32_e32 v176, 0xf0f0f0f0, v115
	v_mfma_i32_4x4x4_16b_i8 v[212:215], v160, v115, v[212:215]
	s_nop 0
	v_mfma_i32_4x4x4_16b_i8 v[216:219], v160, v176, v[216:219]
	v_perm_b32 v160, 0, v161, v190
	s_waitcnt vmcnt(28)
	v_and_b32_e32 v176, 0xf0f0f0f0, v116
	s_nop 0
	v_mfma_i32_4x4x4_16b_i8 v[168:171], v160, v116, v[168:171]
	v_mfma_i32_4x4x4_16b_i8 v[192:195], v160, v176, v[192:195]
	v_and_b32_e32 v176, 0xf0f0f0f0, v117
	v_mfma_i32_4x4x4_16b_i8 v[196:199], v160, v117, v[196:199]
	s_nop 0
	v_mfma_i32_4x4x4_16b_i8 v[200:203], v160, v176, v[200:203]
	v_and_b32_e32 v176, 0xf0f0f0f0, v118
	v_mfma_i32_4x4x4_16b_i8 v[204:207], v160, v118, v[204:207]
	s_nop 0
	v_mfma_i32_4x4x4_16b_i8 v[208:211], v160, v176, v[208:211]
	v_and_b32_e32 v176, 0xf0f0f0f0, v119
	v_mfma_i32_4x4x4_16b_i8 v[212:215], v160, v119, v[212:215]
	s_nop 0
	v_mfma_i32_4x4x4_16b_i8 v[216:219], v160, v176, v[216:219]
	v_perm_b32 v160, 0, v161, v188
	s_waitcnt vmcnt(27)
	v_and_b32_e32 v176, 0xf0f0f0f0, v120
	s_nop 0
	v_mfma_i32_4x4x4_16b_i8 v[168:171], v160, v120, v[168:171]
	v_mfma_i32_4x4x4_16b_i8 v[192:195], v160, v176, v[192:195]
	v_and_b32_e32 v176, 0xf0f0f0f0, v121
	v_mfma_i32_4x4x4_16b_i8 v[196:199], v160, v121, v[196:199]
	s_nop 0
	v_mfma_i32_4x4x4_16b_i8 v[200:203], v160, v176, v[200:203]
	v_and_b32_e32 v176, 0xf0f0f0f0, v122
	v_mfma_i32_4x4x4_16b_i8 v[204:207], v160, v122, v[204:207]
	s_nop 0
	v_mfma_i32_4x4x4_16b_i8 v[208:211], v160, v176, v[208:211]
	v_and_b32_e32 v176, 0xf0f0f0f0, v123
	v_mfma_i32_4x4x4_16b_i8 v[212:215], v160, v123, v[212:215]
	s_nop 0
	v_mfma_i32_4x4x4_16b_i8 v[216:219], v160, v176, v[216:219]
	v_perm_b32 v160, 0, v161, v187
	s_waitcnt vmcnt(26)
	v_and_b32_e32 v161, 0xf0f0f0f0, v124
	s_waitcnt vmcnt(25)
; __device__ __forceinline__ void v_compute(const u32x4 (&w)[16], const PeerVisit& v, bf16* po, int lane) {
;     ...
;     for (int it = 0; it < 16; ++it) {
;         const int A = (int)__builtin_amdgcn_perm(0u, cq[it >> 2], selq[it & 3]);
; #pragma unroll
;         for (int q = 0; q < 4; ++q) {
;             a1[q] = __builtin_amdgcn_mfma_i32_4x4x4i8(A, (int)w[it][q], a1[q], 0, 0, 0);
;             a2[q] = __builtin_amdgcn_mfma_i32_4x4x4i8(A, (int)(w[it][q] & 0xF0F0F0F0u), a2[q], 0, 0, 0);
;         }
;     }
;     int r1[2][4], r2[2][4];
; #pragma unroll
;     for (int jj = 0; jj < 2; ++jj)
; #pragma unroll
;         for (int i = 0; i < 4; ++i) {
;             const auto t1 = __builtin_amdgcn_permlane32_swap((unsigned)a1[jj][i], (unsigned)a1[jj + 2][i], false, false); r1[jj][i] = (int)t1[0] + (int)t1[1];
;             const auto t2 = __builtin_amdgcn_permlane32_swap((unsigned)a2[jj][i], (unsigned)a2[jj + 2][i], false, false); r2[jj][i] = (int)t2[0] + (int)t2[1];
;         }
	v_and_b32_e32 v176, 0xf0f0f0f0, v138
	v_mfma_i32_4x4x4_16b_i8 v[168:171], v160, v124, v[168:171]
	v_mfma_i32_4x4x4_16b_i8 v[192:195], v160, v161, v[192:195]
	v_and_b32_e32 v161, 0xf0f0f0f0, v125
	v_mfma_i32_4x4x4_16b_i8 v[196:199], v160, v125, v[196:199]
	s_nop 0
	v_mfma_i32_4x4x4_16b_i8 v[200:203], v160, v161, v[200:203]
	v_and_b32_e32 v161, 0xf0f0f0f0, v126
	v_mfma_i32_4x4x4_16b_i8 v[204:207], v160, v126, v[204:207]
	s_nop 0
	v_mfma_i32_4x4x4_16b_i8 v[208:211], v160, v161, v[208:211]
	v_and_b32_e32 v161, 0xf0f0f0f0, v127
	v_mfma_i32_4x4x4_16b_i8 v[212:215], v160, v127, v[212:215]
	s_nop 0
	v_mfma_i32_4x4x4_16b_i8 v[216:219], v160, v161, v[216:219]
	v_perm_b32 v160, 0, v162, v189
	s_waitcnt vmcnt(24)
	v_and_b32_e32 v161, 0xf0f0f0f0, v128
	s_nop 0
	v_mfma_i32_4x4x4_16b_i8 v[168:171], v160, v128, v[168:171]
	v_mfma_i32_4x4x4_16b_i8 v[192:195], v160, v161, v[192:195]
	v_and_b32_e32 v161, 0xf0f0f0f0, v129
	v_mfma_i32_4x4x4_16b_i8 v[196:199], v160, v129, v[196:199]
	s_nop 0
	v_mfma_i32_4x4x4_16b_i8 v[200:203], v160, v161, v[200:203]
	v_and_b32_e32 v161, 0xf0f0f0f0, v130
	v_mfma_i32_4x4x4_16b_i8 v[204:207], v160, v130, v[204:207]
	s_nop 0
	v_mfma_i32_4x4x4_16b_i8 v[208:211], v160, v161, v[208:211]
	v_and_b32_e32 v161, 0xf0f0f0f0, v131
	v_mfma_i32_4x4x4_16b_i8 v[212:215], v160, v131, v[212:215]
	s_nop 0
	v_mfma_i32_4x4x4_16b_i8 v[216:219], v160, v161, v[216:219]
	v_perm_b32 v160, 0, v162, v190
	s_waitcnt vmcnt(23)
	v_and_b32_e32 v161, 0xf0f0f0f0, v132
	s_nop 0
	v_mfma_i32_4x4x4_16b_i8 v[168:171], v160, v132, v[168:171]
	v_mfma_i32_4x4x4_16b_i8 v[192:195], v160, v161, v[192:195]
	v_and_b32_e32 v161, 0xf0f0f0f0, v133
	v_mfma_i32_4x4x4_16b_i8 v[196:199], v160, v133, v[196:199]
	s_nop 0
	v_mfma_i32_4x4x4_16b_i8 v[200:203], v160, v161, v[200:203]
	v_and_b32_e32 v161, 0xf0f0f0f0, v134
	v_mfma_i32_4x4x4_16b_i8 v[204:207], v160, v134, v[204:207]
	s_nop 0
	v_mfma_i32_4x4x4_16b_i8 v[208:211], v160, v161, v[208:211]
	v_and_b32_e32 v161, 0xf0f0f0f0, v135
	v_mfma_i32_4x4x4_16b_i8 v[212:215], v160, v135, v[212:215]
	s_nop 0
	v_mfma_i32_4x4x4_16b_i8 v[216:219], v160, v161, v[216:219]
	v_perm_b32 v160, 0, v162, v188
	v_perm_b32 v162, 0, v162, v187
	v_and_b32_e32 v161, 0xf0f0f0f0, v136
	v_mfma_i32_4x4x4_16b_i8 v[208:211], v160, v176, v[208:211]
	v_and_b32_e32 v176, 0xf0f0f0f0, v140
	v_mfma_i32_4x4x4_16b_i8 v[192:195], v160, v161, v[192:195]
	v_and_b32_e32 v161, 0xf0f0f0f0, v137
	v_mfma_i32_4x4x4_16b_i8 v[204:207], v160, v138, v[204:207]
	v_perm_b32 v187, 0, v163, v187
	v_mfma_i32_4x4x4_16b_i8 v[192:195], v162, v176, v[192:195]
	v_perm_b32 v176, 0, v163, v189
	v_mfma_i32_4x4x4_16b_i8 v[200:203], v160, v161, v[200:203]
	v_and_b32_e32 v161, 0xf0f0f0f0, v139
	v_mfma_i32_4x4x4_16b_i8 v[168:171], v160, v136, v[168:171]
	v_and_b32_e32 v189, 0xf0f0f0f0, v146
	v_mfma_i32_4x4x4_16b_i8 v[196:199], v160, v137, v[196:199]
	v_mfma_i32_4x4x4_16b_i8 v[212:215], v160, v139, v[212:215]
	v_mfma_i32_4x4x4_16b_i8 v[216:219], v160, v161, v[216:219]
	v_and_b32_e32 v160, 0xf0f0f0f0, v142
	v_mfma_i32_4x4x4_16b_i8 v[204:207], v162, v142, v[204:207]
	v_and_b32_e32 v161, 0xf0f0f0f0, v143
	v_mfma_i32_4x4x4_16b_i8 v[208:211], v162, v160, v[208:211]
	v_and_b32_e32 v160, 0xf0f0f0f0, v148
	v_mfma_i32_4x4x4_16b_i8 v[168:171], v162, v140, v[168:171]
	v_mfma_i32_4x4x4_16b_i8 v[190:193], v176, v183, v[192:195]
	v_and_b32_e32 v183, 0xf0f0f0f0, v151
	v_mfma_i32_4x4x4_16b_i8 v[204:207], v176, v146, v[204:207]
	v_mfma_i32_4x4x4_16b_i8 v[208:211], v176, v189, v[208:211]
	v_mfma_i32_4x4x4_16b_i8 v[216:219], v162, v161, v[216:219]
	v_and_b32_e32 v161, 0xf0f0f0f0, v150
	v_mfma_i32_4x4x4_16b_i8 v[168:171], v176, v144, v[168:171]
	v_mfma_i32_4x4x4_16b_i8 v[188:191], v221, v160, v[190:193]
	v_mfma_i32_4x4x4_16b_i8 v[192:195], v221, v150, v[204:207]
	v_mfma_i32_4x4x4_16b_i8 v[204:207], v221, v161, v[208:211]
	v_mfma_i32_4x4x4_16b_i8 v[196:199], v162, v141, v[196:199]
	v_and_b32_e32 v208, 0xf0f0f0f0, v156
	v_mfma_i32_4x4x4_16b_i8 v[200:203], v162, v182, v[200:203]
	v_and_b32_e32 v182, 0xf0f0f0f0, v145
	v_mfma_i32_4x4x4_16b_i8 v[212:215], v162, v143, v[212:215]
	v_and_b32_e32 v162, 0xf0f0f0f0, v152
	v_mfma_i32_4x4x4_16b_i8 v[168:171], v221, v148, v[168:171]
	s_nop 0
	v_mfma_i32_4x4x4_16b_i8 v[160:163], v223, v162, v[188:191]
	v_mfma_i32_4x4x4_16b_i8 v[188:191], v223, v154, v[192:195]
	v_mfma_i32_4x4x4_16b_i8 v[192:195], v223, v225, v[204:207]
	v_and_b32_e32 v225, 0xf0f0f0f0, v159
	v_mfma_i32_4x4x4_16b_i8 v[168:171], v223, v152, v[168:171]
	v_and_b32_e32 v204, 0xf0f0f0f0, v158
	v_mfma_i32_4x4x4_16b_i8 v[160:163], v187, v208, v[160:163]
	s_nop 0
	v_mfma_i32_4x4x4_16b_i8 v[192:195], v187, v204, v[192:195]
	v_mfma_i32_4x4x4_16b_i8 v[196:199], v176, v145, v[196:199]
	v_mfma_i32_4x4x4_16b_i8 v[200:203], v176, v182, v[200:203]
	v_mfma_i32_4x4x4_16b_i8 v[204:207], v176, v147, v[212:215]
	s_nop 1
	v_permlane32_swap_b32_e32 v160, v192
	v_mfma_i32_4x4x4_16b_i8 v[208:211], v176, v220, v[216:219]
	v_permlane32_swap_b32_e32 v161, v193
	v_mfma_i32_4x4x4_16b_i8 v[168:171], v187, v156, v[168:171]
	v_permlane32_swap_b32_e32 v162, v194
	v_mfma_i32_4x4x4_16b_i8 v[188:191], v187, v158, v[188:191]
; __device__ __forceinline__ unsigned cvt_pk_bf16(float lo, float hi) { unsigned r; asm volatile("v_cvt_pk_bf16_f32 %0, %1, %2" : "=v"(r) : "v"(lo), "v"(hi)); return r; }
; __device__ __forceinline__ void v_compute(const u32x4 (&w)[16], const PeerVisit& v, bf16* po, int lane) {
;     ...
;     int r1[2][4], r2[2][4];
; #pragma unroll
;     for (int jj = 0; jj < 2; ++jj)
; #pragma unroll
;         for (int i = 0; i < 4; ++i) {
;             const auto t1 = __builtin_amdgcn_permlane32_swap((unsigned)a1[jj][i], (unsigned)a1[jj + 2][i], false, false); r1[jj][i] = (int)t1[0] + (int)t1[1];
;             const auto t2 = __builtin_amdgcn_permlane32_swap((unsigned)a2[jj][i], (unsigned)a2[jj + 2][i], false, false); r2[jj][i] = (int)t2[0] + (int)t2[1];
;         }
;     int s1[4], s2[4];
; #pragma unroll
;     for (int i = 0; i < 4; ++i) {
;         const auto t1 = __builtin_amdgcn_permlane16_swap((unsigned)r1[0][i], (unsigned)r1[1][i], false, false); s1[i] = (int)t1[0] + (int)t1[1];
;         const auto t2 = __builtin_amdgcn_permlane16_swap((unsigned)r2[0][i], (unsigned)r2[1][i], false, false); s2[i] = (int)t2[0] + (int)t2[1];
;         s1[i] += __builtin_amdgcn_update_dpp(0, s1[i], 0x128, 0xF, 0xF, false);
;         s2[i] += __builtin_amdgcn_update_dpp(0, s2[i], 0x128, 0xF, 0xF, false);
;     }
;     if (!(lane & 8)) {
;         const float csf = (float)v.cs; float lo[4], hi[4];
; #pragma unroll
;         for (int i = 0; i < 4; ++i) { lo[i] = ((float)(s1[i] - s2[i]) - 7.5f * csf) * v.sc; hi[i] = ((float)s2[i] * 0.0625f + 0.5f * csf) * v.sc; }
;         u32x4 o;
;         o.x = cvt_pk_bf16(lo[0], lo[1]); o.y = cvt_pk_bf16(lo[2], lo[3]); o.z = cvt_pk_bf16(hi[0], hi[1]); o.w = cvt_pk_bf16(hi[2], hi[3]);
;         __builtin_nontemporal_store(o, (u32x4*)(po + (lane & 7) * 32 + 8 * (((lane >> 4) & 1) + 2 * (lane >> 5))));
;     }
	v_permlane32_swap_b32_e32 v163, v195
	v_mfma_i32_4x4x4_16b_i8 v[196:199], v221, v149, v[196:199]
	v_add_u32_e32 v229, v160, v192
	v_mfma_i32_4x4x4_16b_i8 v[200:203], v221, v222, v[200:203]
	s_nop 0
	v_permlane32_swap_b32_e32 v168, v188
	v_mfma_i32_4x4x4_16b_i8 v[204:207], v221, v151, v[204:207]
	v_permlane32_swap_b32_e32 v169, v189
	v_mfma_i32_4x4x4_16b_i8 v[208:211], v221, v183, v[208:211]
	v_permlane32_swap_b32_e32 v170, v190
	v_permlane32_swap_b32_e32 v171, v191
	v_add_u32_e32 v228, v168, v188
	v_add_u32_e32 v182, v169, v189
	v_add_u32_e32 v212, v170, v190
	v_mfma_i32_4x4x4_16b_i8 v[196:199], v223, v153, v[196:199]
	v_add_u32_e32 v213, v171, v191
	v_mfma_i32_4x4x4_16b_i8 v[200:203], v223, v224, v[200:203]
	v_add_u32_e32 v176, v161, v193
	v_mfma_i32_4x4x4_16b_i8 v[204:207], v223, v155, v[204:207]
	v_add_u32_e32 v183, v162, v194
	v_mfma_i32_4x4x4_16b_i8 v[168:171], v223, v226, v[208:211]
	v_mfma_i32_4x4x4_16b_i8 v[188:191], v187, v157, v[196:199]
	s_nop 0
	v_add_u32_e32 v196, v163, v195
	v_mfma_i32_4x4x4_16b_i8 v[160:163], v187, v159, v[204:207]
	v_mfma_i32_4x4x4_16b_i8 v[192:195], v187, v227, v[200:203]
	v_mfma_i32_4x4x4_16b_i8 v[168:171], v187, v225, v[168:171]
	s_nop 2
	v_permlane32_swap_b32_e32 v188, v160
	v_permlane32_swap_b32_e32 v189, v161
	v_permlane32_swap_b32_e32 v192, v168
	v_permlane32_swap_b32_e32 v193, v169
	v_permlane32_swap_b32_e32 v190, v162
	v_permlane32_swap_b32_e32 v194, v170
	v_permlane32_swap_b32_e32 v191, v163
	v_permlane32_swap_b32_e32 v195, v171
	v_add_u32_e32 v160, v188, v160
	v_add_u32_e32 v168, v192, v168
	v_add_u32_e32 v187, v189, v161
	v_add_u32_e32 v169, v193, v169
	v_add_u32_e32 v188, v190, v162
	v_add_u32_e32 v189, v194, v170
	v_add_u32_e32 v190, v191, v163
	v_add_u32_e32 v191, v195, v171
	v_permlane16_swap_b32_e32 v228, v160
	v_permlane16_swap_b32_e32 v229, v168
	v_permlane16_swap_b32_e32 v182, v187
	v_permlane16_swap_b32_e32 v176, v169
	v_permlane16_swap_b32_e32 v212, v188
	v_permlane16_swap_b32_e32 v183, v189
	v_permlane16_swap_b32_e32 v213, v190
	v_permlane16_swap_b32_e32 v196, v191
	v_add_u32_e32 v160, v228, v160
	v_add_u32_e32 v161, v229, v168
	v_mov_b32_e32 v162, 0
	v_mov_b32_e32 v163, 0
	v_add_u32_e32 v168, v182, v187
	v_add_u32_e32 v169, v176, v169
	v_mov_b32_e32 v170, 0
	v_mov_b32_e32 v171, 0
	v_add_u32_e32 v176, v212, v188
	v_add_u32_e32 v182, v183, v189
	v_mov_b32_e32 v183, 0
	v_mov_b32_e32 v187, 0
	v_add_u32_e32 v188, v213, v190
	v_add_u32_e32 v189, v196, v191
	v_mov_b32_e32 v190, 0
	v_mov_b32_e32 v191, 0
	v_mov_b32_dpp v162, v160 row_ror:8 row_mask:0xf bank_mask:0xf
	v_mov_b32_dpp v163, v161 row_ror:8 row_mask:0xf bank_mask:0xf
	v_mov_b32_dpp v170, v168 row_ror:8 row_mask:0xf bank_mask:0xf
	v_mov_b32_dpp v171, v169 row_ror:8 row_mask:0xf bank_mask:0xf
	v_mov_b32_dpp v183, v176 row_ror:8 row_mask:0xf bank_mask:0xf
	v_mov_b32_dpp v187, v182 row_ror:8 row_mask:0xf bank_mask:0xf
	v_mov_b32_dpp v190, v188 row_ror:8 row_mask:0xf bank_mask:0xf
	v_mov_b32_dpp v191, v189 row_ror:8 row_mask:0xf bank_mask:0xf
	s_and_saveexec_b64 s[44:45], s[40:41]
	s_cbranch_execz .LBB0_2140
	v_add_u32_e32 v161, v163, v161
	v_add_u32_e32 v160, v162, v160
	v_add_u32_e32 v169, v171, v169
	v_add_u32_e32 v168, v170, v168
	v_sub_u32_e32 v160, v160, v161
	v_cvt_f32_i32_e32 v162, v160
	v_sub_u32_e32 v160, v168, v169
	v_add_u32_e32 v182, v187, v182
	v_add_u32_e32 v176, v183, v176
	v_cvt_f32_i32_e32 v168, v160
	v_cvt_f32_i32_e32 v160, v179
	v_cvt_f32_i32_e32 v170, v161
	v_sub_u32_e32 v163, v176, v182
	v_cvt_f32_i32_e32 v161, v182
	v_cvt_f32_i32_e32 v171, v163
	v_cvt_f32_i32_e32 v169, v169
	v_fmac_f32_e32 v162, 0xc0f00000, v160
	v_mul_f32_e32 v176, v178, v162
	v_pk_mul_f32 v[162:163], v[160:161], s[42:43]
	v_add_u32_e32 v189, v191, v189
	v_add_u32_e32 v188, v190, v188
	v_fmamk_f32 v161, v170, 0x3d800000, v162
	v_fmac_f32_e32 v168, 0xc0f00000, v160
	v_fmac_f32_e32 v171, 0xc0f00000, v160
	v_mul_f32_e32 v170, v178, v161
	v_mul_f32_e32 v161, v178, v168
	v_fmamk_f32 v168, v169, 0x3d800000, v162
	v_mul_f32_e32 v169, v178, v171
	v_sub_u32_e32 v171, v188, v189
	v_cvt_f32_i32_e32 v171, v171
	v_cvt_f32_i32_e32 v179, v189
	s_add_i32 s40, s90, s70
	s_ashr_i32 s41, s40, 31
	v_fmac_f32_e32 v171, 0xc0f00000, v160
	v_mul_f32_e32 v171, v178, v171
	v_add_f32_e32 v163, v162, v163
	v_fmac_f32_e32 v162, 0x3d800000, v179
	v_cvt_pk_bf16_f32 v160, v176, v161
	v_cvt_pk_bf16_f32 v161, v169, v171
	v_ashrrev_i32_e32 v171, 4, v186
	s_lshl_b64 s[40:41], s[40:41], 12
	v_mul_f32_e32 v168, v178, v168
	v_mul_f32_e32 v163, v178, v163
	v_mul_f32_e32 v178, v178, v162
	v_cvt_pk_bf16_f32 v162, v170, v168
	v_lshrrev_b32_e32 v170, 4, v186
	v_and_b32_e32 v171, 0x1ffffffe, v171
	s_add_u32 s40, s62, s40
	v_lshlrev_b32_e32 v168, 6, v186
	v_and_or_b32 v170, v170, 1, v171
	s_addc_u32 s41, s63, s41
	v_and_b32_e32 v176, 0x1c0, v168
	v_lshlrev_b32_e32 v170, 3, v170
	v_lshl_add_u64 v[168:169], s[40:41], 0, v[176:177]
	v_ashrrev_i32_e32 v171, 31, v170
	v_lshl_add_u64 v[168:169], v[170:171], 1, v[168:169]
	v_cvt_pk_bf16_f32 v163, v163, v178
	global_store_dwordx4 v[168:169], v[160:163], off nt
	s_branch .LBB0_2140
